# attention output epilogue: normalise + transpose through dead K LDS buffers, 8 x 16-byte row stores per lane instead of 64 2-byte stores
# baseline (speedup 1.0000x reference)
; #define SBAR() __builtin_amdgcn_sched_barrier(0)
; template <int OFF> __device__ __forceinline__ s16x4 tr_read(int vb) { s16x4 r; asm volatile("ds_read_b64_tr_b16 %0, %1 offset:%2" : "=&v"(r) : "v"(vb), "i"(OFF) : "memory"); return r; }
; __device__ __forceinline__ void finishSM(f32x16& p0, f32x16& p1, float alpha, float& l_reg, bf16x8& pa0, bf16x8& pa1, bf16x8& pa2, bf16x8& pa3) {
;     ...
;     for (int r = 0; r < 16; ++r) p1[r] = __builtin_amdgcn_exp2f(p1[r]);
;     float ps = 0;
; #pragma unroll
;     for (int r = 0; r < 16; ++r) ps += p0[r];
; #pragma unroll
;     for (int r = 0; r < 16; ++r) ps += p1[r];
;     { auto rr = __builtin_amdgcn_permlane32_swap(__float_as_uint(ps), __float_as_uint(ps), false, false); ps = __uint_as_float(rr[0]) + __uint_as_float(rr[1]); }
;     l_reg = l_reg * alpha + ps;
;     ...
;     PK4(p0, 0, pa0); PK4(p0, 8, pa1); PK4(p1, 0, pa2); PK4(p1, 8, pa3);
; template <int D0> __device__ __forceinline__ void pv_one(f32x16& od, int vb, bf16x8 pa0, bf16x8 pa1, bf16x8 pa2, bf16x8 pa3) {
;     const s16x4 l0 = tr_read<v_rd_off(D0, 0, 0)>(vb), h0 = tr_read<v_rd_off(D0, 0, 1)>(vb), l1 = tr_read<v_rd_off(D0, 1, 0)>(vb), h1 = tr_read<v_rd_off(D0, 1, 1)>(vb);
;     const s16x4 l2 = tr_read<v_rd_off(D0, 2, 0)>(vb), h2 = tr_read<v_rd_off(D0, 2, 1)>(vb), l3 = tr_read<v_rd_off(D0, 3, 0)>(vb), h3 = tr_read<v_rd_off(D0, 3, 1)>(vb);
;     asm volatile("s_waitcnt lgkmcnt(0)" ::: "memory"); SBAR();
;     ...
;     od = __builtin_amdgcn_mfma_f32_32x32x16_bf16(pa0, PK(l0, h0), od, 0, 0, 0);
;     od = __builtin_amdgcn_mfma_f32_32x32x16_bf16(pa1, PK(l1, h1), od, 0, 0, 0);
;     od = __builtin_amdgcn_mfma_f32_32x32x16_bf16(pa2, PK(l2, h2), od, 0, 0, 0);
;     od = __builtin_amdgcn_mfma_f32_32x32x16_bf16(pa3, PK(l3, h3), od, 0, 0, 0);
;     ...
; }
; __device__ __forceinline__ void pv_d0(f32x16* o, int vb, bf16x8 pa0, bf16x8 pa1, bf16x8 pa2, bf16x8 pa3) {
;     pv_one<0>(o[0], vb, pa0, pa1, pa2, pa3); pv_one<1>(o[1], vb, pa0, pa1, pa2, pa3); pv_one<2>(o[2], vb, pa0, pa1, pa2, pa3); pv_one<3>(o[3], vb, pa0, pa1, pa2, pa3);
.LBB0_1395:
	v_cndmask_b32_e64 v99, v99, v158, s[4:5]
	v_sub_f32_e32 v80, v80, v99
	v_sub_f32_e32 v81, v81, v99
	v_sub_f32_e32 v105, v93, v99
	v_exp_f32_e32 v93, v80
	v_sub_f32_e32 v82, v82, v99
	v_sub_f32_e32 v107, v95, v99
	v_exp_f32_e32 v95, v81
	v_sub_f32_e32 v83, v83, v99
	v_sub_f32_e32 v103, v91, v99
	v_exp_f32_e32 v91, v82
	v_sub_f32_e32 v84, v84, v99
	v_sub_f32_e32 v106, v94, v99
	v_exp_f32_e32 v94, v83
	v_sub_f32_e32 v64, v64, v99
	v_sub_f32_e32 v85, v85, v99
	v_sub_f32_e32 v86, v86, v99
	v_sub_f32_e32 v87, v87, v99
	v_sub_f32_e32 v100, v88, v99
	v_sub_f32_e32 v101, v89, v99
	v_sub_f32_e32 v102, v90, v99
	v_sub_f32_e32 v104, v92, v99
	v_exp_f32_e32 v89, v84
	v_sub_f32_e32 v65, v65, v99
	v_sub_f32_e32 v66, v66, v99
	v_sub_f32_e32 v67, v67, v99
	v_sub_f32_e32 v68, v68, v99
	v_sub_f32_e32 v69, v69, v99
	v_sub_f32_e32 v70, v70, v99
	v_sub_f32_e32 v71, v71, v99
	v_sub_f32_e32 v72, v72, v99
	v_sub_f32_e32 v73, v73, v99
	v_sub_f32_e32 v74, v74, v99
	v_sub_f32_e32 v75, v75, v99
	v_sub_f32_e32 v76, v76, v99
	v_sub_f32_e32 v77, v77, v99
	v_sub_f32_e32 v78, v78, v99
	v_sub_f32_e32 v79, v79, v99
	v_exp_f32_e32 v99, v64
	v_add_f32_e32 v64, 0, v93
	v_exp_f32_e32 v92, v85
	v_add_f32_e32 v64, v95, v64
	v_exp_f32_e32 v88, v86
	v_add_f32_e32 v64, v91, v64
	v_exp_f32_e32 v90, v87
	v_add_f32_e32 v64, v94, v64
	v_exp_f32_e32 v85, v100
	v_add_f32_e32 v64, v89, v64
	v_exp_f32_e32 v87, v101
	v_add_f32_e32 v64, v92, v64
	v_exp_f32_e32 v83, v102
	v_add_f32_e32 v64, v88, v64
	v_exp_f32_e32 v86, v103
	v_add_f32_e32 v64, v90, v64
	v_exp_f32_e32 v81, v104
	v_add_f32_e32 v64, v85, v64
	v_exp_f32_e32 v84, v105
	v_add_f32_e32 v64, v87, v64
	v_exp_f32_e32 v80, v106
	v_add_f32_e32 v64, v83, v64
	v_exp_f32_e32 v82, v107
	v_add_f32_e32 v64, v86, v64
	v_add_f32_e32 v64, v81, v64
	v_exp_f32_e32 v100, v65
	v_add_f32_e32 v64, v84, v64
	v_exp_f32_e32 v101, v66
	v_add_f32_e32 v64, v80, v64
	v_exp_f32_e32 v102, v67
	v_add_f32_e32 v64, v82, v64
	v_exp_f32_e32 v103, v68
	v_add_f32_e32 v64, v99, v64
	v_exp_f32_e32 v104, v69
	v_add_f32_e32 v64, v100, v64
	v_exp_f32_e32 v105, v70
	v_add_f32_e32 v64, v101, v64
	v_exp_f32_e32 v106, v71
	v_add_f32_e32 v64, v102, v64
	v_exp_f32_e32 v107, v72
	v_add_f32_e32 v64, v103, v64
	v_exp_f32_e32 v108, v73
	v_add_f32_e32 v64, v104, v64
	v_exp_f32_e32 v109, v74
	v_add_f32_e32 v64, v105, v64
	v_exp_f32_e32 v110, v75
	v_add_f32_e32 v64, v106, v64
	v_exp_f32_e32 v111, v76
	v_add_f32_e32 v64, v107, v64
	v_exp_f32_e32 v112, v77
	v_add_f32_e32 v64, v108, v64
	v_exp_f32_e32 v113, v78
	v_add_f32_e32 v64, v109, v64
	v_exp_f32_e32 v114, v79
	v_add_f32_e32 v64, v110, v64
	v_add_f32_e32 v64, v111, v64
	v_add_f32_e32 v64, v112, v64
	v_add_f32_e32 v64, v113, v64
	v_add_f32_e32 v64, v114, v64
	v_mov_b32_e32 v65, v64
	s_nop 1
	v_permlane32_swap_b32_e32 v64, v65
	v_cvt_pk_bf16_f32 v66, v93, v95
	v_cvt_pk_bf16_f32 v67, v91, v94
	v_cvt_pk_bf16_f32 v68, v89, v92
	v_cvt_pk_bf16_f32 v69, v88, v90
	v_cvt_pk_bf16_f32 v70, v85, v87
	v_cvt_pk_bf16_f32 v71, v83, v86
	v_cvt_pk_bf16_f32 v72, v81, v84
	v_cvt_pk_bf16_f32 v73, v80, v82
	v_cvt_pk_bf16_f32 v74, v99, v100
	v_cvt_pk_bf16_f32 v75, v101, v102
	v_cvt_pk_bf16_f32 v76, v103, v104
	v_cvt_pk_bf16_f32 v77, v105, v106
	v_cvt_pk_bf16_f32 v78, v107, v108
	v_cvt_pk_bf16_f32 v79, v109, v110
	v_cvt_pk_bf16_f32 v80, v111, v112
	v_cvt_pk_bf16_f32 v81, v113, v114
	s_nop 0
	v_permlane32_swap_b32_e32 v66, v68
	v_permlane32_swap_b32_e32 v67, v69
	v_permlane32_swap_b32_e32 v70, v72
	v_permlane32_swap_b32_e32 v71, v73
	v_permlane32_swap_b32_e32 v74, v76
	v_permlane32_swap_b32_e32 v75, v77
	v_permlane32_swap_b32_e32 v78, v80
	v_permlane32_swap_b32_e32 v79, v81
	ds_read_b64_tr_b16 v[82:83], v175 offset:0
	ds_read_b64_tr_b16 v[84:85], v175 offset:0x800
	ds_read_b64_tr_b16 v[86:87], v175 offset:0x1000
	ds_read_b64_tr_b16 v[88:89], v175 offset:0x1800
	ds_read_b64_tr_b16 v[90:91], v175 offset:0x2000
	ds_read_b64_tr_b16 v[92:93], v175 offset:0x2800
	ds_read_b64_tr_b16 v[100:101], v175 offset:0x3000
	ds_read_b64_tr_b16 v[102:103], v175 offset:0x3800
	s_waitcnt lgkmcnt(0)
	s_nop 0
	v_mfma_f32_32x32x16_bf16 v[0:15], v[66:69], v[82:85], v[0:15]
	ds_read_b64_tr_b16 v[82:83], v175 offset:0x200
	ds_read_b64_tr_b16 v[84:85], v175 offset:0xa00
	v_mfma_f32_32x32x16_bf16 v[0:15], v[70:73], v[86:89], v[0:15]
	ds_read_b64_tr_b16 v[86:87], v175 offset:0x1200
	ds_read_b64_tr_b16 v[88:89], v175 offset:0x1a00
	v_mfma_f32_32x32x16_bf16 v[0:15], v[74:77], v[90:93], v[0:15]
	ds_read_b64_tr_b16 v[90:91], v175 offset:0x2200
	ds_read_b64_tr_b16 v[92:93], v175 offset:0x2a00
	v_mfma_f32_32x32x16_bf16 v[0:15], v[78:81], v[100:103], v[0:15]
	ds_read_b64_tr_b16 v[100:101], v175 offset:0x3200
	ds_read_b64_tr_b16 v[102:103], v175 offset:0x3a00
	s_waitcnt lgkmcnt(0)
	v_mfma_f32_32x32x16_bf16 v[48:63], v[66:69], v[82:85], v[48:63]
	ds_read_b64_tr_b16 v[82:83], v175 offset:0x400
	ds_read_b64_tr_b16 v[84:85], v175 offset:0xc00
	v_mfma_f32_32x32x16_bf16 v[48:63], v[70:73], v[86:89], v[48:63]
	ds_read_b64_tr_b16 v[86:87], v175 offset:0x1400
	ds_read_b64_tr_b16 v[88:89], v175 offset:0x1c00
	v_mfma_f32_32x32x16_bf16 v[48:63], v[74:77], v[90:93], v[48:63]
	ds_read_b64_tr_b16 v[90:91], v175 offset:0x2400
	ds_read_b64_tr_b16 v[92:93], v175 offset:0x2c00
	v_mfma_f32_32x32x16_bf16 v[48:63], v[78:81], v[100:103], v[48:63]
	ds_read_b64_tr_b16 v[100:101], v175 offset:0x3400
	ds_read_b64_tr_b16 v[102:103], v175 offset:0x3c00
	s_waitcnt lgkmcnt(0)
; __device__ __forceinline__ bf16_t f2bf(float f) { return (bf16_t)(cvt_pk_bf16(f, 0.f) & 0xffffu); }
; #define SBAR() __builtin_amdgcn_sched_barrier(0)
; __device__ __forceinline__ int crow(int r, int hi) { return (r & 3) + 8 * (r >> 2) + 4 * hi; }
; template <int OFF> __device__ __forceinline__ s16x4 tr_read(int vb) { s16x4 r; asm volatile("ds_read_b64_tr_b16 %0, %1 offset:%2" : "=&v"(r) : "v"(vb), "i"(OFF) : "memory"); return r; }
; template <int D0> __device__ __forceinline__ void pv_one(f32x16& od, int vb, bf16x8 pa0, bf16x8 pa1, bf16x8 pa2, bf16x8 pa3) {
;     const s16x4 l0 = tr_read<v_rd_off(D0, 0, 0)>(vb), h0 = tr_read<v_rd_off(D0, 0, 1)>(vb), l1 = tr_read<v_rd_off(D0, 1, 0)>(vb), h1 = tr_read<v_rd_off(D0, 1, 1)>(vb);
;     const s16x4 l2 = tr_read<v_rd_off(D0, 2, 0)>(vb), h2 = tr_read<v_rd_off(D0, 2, 1)>(vb), l3 = tr_read<v_rd_off(D0, 3, 0)>(vb), h3 = tr_read<v_rd_off(D0, 3, 1)>(vb);
;     asm volatile("s_waitcnt lgkmcnt(0)" ::: "memory"); SBAR();
;     ...
;     od = __builtin_amdgcn_mfma_f32_32x32x16_bf16(pa0, PK(l0, h0), od, 0, 0, 0);
;     od = __builtin_amdgcn_mfma_f32_32x32x16_bf16(pa1, PK(l1, h1), od, 0, 0, 0);
;     od = __builtin_amdgcn_mfma_f32_32x32x16_bf16(pa2, PK(l2, h2), od, 0, 0, 0);
;     od = __builtin_amdgcn_mfma_f32_32x32x16_bf16(pa3, PK(l3, h3), od, 0, 0, 0);
; __device__ __forceinline__ void attn_unit(const bf16_t* __restrict__ Qb, const bf16_t* __restrict__ Kh, const bf16_t* __restrict__ Vh, bf16_t* __restrict__ Ob, int seq, char* lds) {
;     ...
;     pv_d0(o, vb0 + SHM_V, pa0, pa1, pa2, pa3);
;     if (hi == 0) li_l[r32] = l_reg; asm volatile("s_waitcnt lgkmcnt(0)" ::: "memory");
;     float rli[16];
; #pragma unroll
;     for (int r = 0; r < 16; ++r) rli[r] = __builtin_amdgcn_rcpf(li_l[crow(r, hi)]);
;     bf16_t* Ow = Ob + (size_t)(wid * QBLK) * 2048;
; #pragma unroll
;     for (int r = 0; r < 16; ++r) { const int orow = crow(r, hi);
; #pragma unroll
;         for (int d0 = 0; d0 < 4; ++d0) Ow[(size_t)orow * 2048 + d0 * 32 + r32] = f2bf(o[d0][r] * rli[r]); }
	v_mfma_f32_32x32x16_bf16 v[32:47], v[66:69], v[82:85], v[32:47]
	ds_read_b64_tr_b16 v[82:83], v175 offset:0x600
	ds_read_b64_tr_b16 v[84:85], v175 offset:0xe00
	v_mfma_f32_32x32x16_bf16 v[32:47], v[70:73], v[86:89], v[32:47]
	ds_read_b64_tr_b16 v[86:87], v175 offset:0x1600
	ds_read_b64_tr_b16 v[88:89], v175 offset:0x1e00
	v_mfma_f32_32x32x16_bf16 v[32:47], v[74:77], v[90:93], v[32:47]
	ds_read_b64_tr_b16 v[90:91], v175 offset:0x2600
	ds_read_b64_tr_b16 v[92:93], v175 offset:0x2e00
	v_mfma_f32_32x32x16_bf16 v[32:47], v[78:81], v[100:103], v[32:47]
	ds_read_b64_tr_b16 v[100:101], v175 offset:0x3600
	ds_read_b64_tr_b16 v[102:103], v175 offset:0x3e00
	s_waitcnt lgkmcnt(0)
	v_mfma_f32_32x32x16_bf16 v[16:31], v[66:69], v[82:85], v[16:31]
	v_mfma_f32_32x32x16_bf16 v[16:31], v[70:73], v[86:89], v[16:31]
	v_mfma_f32_32x32x16_bf16 v[16:31], v[74:77], v[90:93], v[16:31]
	v_mfma_f32_32x32x16_bf16 v[16:31], v[78:81], v[100:103], v[16:31]
	s_and_saveexec_b64 s[4:5], s[2:3]
	v_add_f32_e32 v66, v96, v97
	v_fmac_f32_e32 v66, v174, v140
	v_add_f32_e32 v64, v64, v65
	v_fmac_f32_e32 v64, v66, v98
	ds_write_b32 v173, v64
	s_or_b64 exec, exec, s[4:5]
	s_waitcnt lgkmcnt(0)
	v_add_u32_e32 v72, v149, v160
	ds_read_b128 v[64:67], v72
	ds_read_b128 v[68:71], v72 offset:32
	ds_read_b128 v[74:77], v72 offset:64
	ds_read_b128 v[78:81], v72 offset:96
	s_lshl_b64 s[2:3], s[10:11], 12
	s_add_u32 s2, s68, s2
	s_addc_u32 s3, s69, s3
	s_lshl_b32 s4, s48, 1
	s_add_u32 s2, s2, s4
	s_addc_u32 s3, s3, 0
	s_add_u32 s2, s2, 0x2cf00000
	s_addc_u32 s3, s3, 0
	v_readfirstlane_b32 s4, v148
	v_lshlrev_b32_e32 v82, 8, v148
	v_add_u32_e32 v82, 0x8000, v82
	v_lshl_add_u32 v83, v172, 10, v82
	v_lshl_add_u32 v83, v159, 1, v83
	v_lshlrev_b32_e32 v84, 6, v172
	v_add_u32_e32 v85, v83, v84
	v_sub_u32_e32 v86, v83, v84
	v_and_b32_e32 v87, 63, v206
	v_lshrrev_b32_e32 v88, 4, v87
	v_and_b32_e32 v89, 15, v87
	v_lshl_add_u32 v90, v88, 8, v82
	v_lshlrev_b32_e32 v91, 4, v89
	v_xor_b32_e32 v92, 64, v91
	v_add_u32_e32 v93, v90, v91
	v_add_u32_e32 v94, v90, v92
	v_lshlrev_b32_e32 v95, 12, v88
	v_add_u32_e32 v95, v95, v91
	s_lshl_b32 s4, s4, 12
	s_add_u32 s2, s2, s4
	s_addc_u32 s3, s3, 0
	s_waitcnt lgkmcnt(0)
	v_rcp_f32_e32 v64, v64
	v_rcp_f32_e32 v65, v65
	v_rcp_f32_e32 v66, v66
	v_rcp_f32_e32 v67, v67
	v_rcp_f32_e32 v68, v68
	v_rcp_f32_e32 v69, v69
	v_rcp_f32_e32 v70, v70
	v_rcp_f32_e32 v71, v71
	v_rcp_f32_e32 v74, v74
	v_rcp_f32_e32 v75, v75
	v_rcp_f32_e32 v76, v76
	v_rcp_f32_e32 v77, v77
	v_rcp_f32_e32 v78, v78
	v_rcp_f32_e32 v79, v79
	v_rcp_f32_e32 v80, v80
	v_rcp_f32_e32 v81, v81
	v_mul_f32_e32 v0, v0, v64
	v_mul_f32_e32 v48, v48, v64
	v_cvt_pk_bf16_f32 v100, v0, v48
	ds_write_b16 v85, v100 offset:0
	ds_write_b16_d16_hi v86, v100 offset:64
	v_mul_f32_e32 v32, v32, v64
	v_mul_f32_e32 v16, v16, v64
	v_cvt_pk_bf16_f32 v101, v32, v16
	ds_write_b16 v85, v101 offset:128
	ds_write_b16_d16_hi v86, v101 offset:192
	v_mul_f32_e32 v1, v1, v65
	v_mul_f32_e32 v49, v49, v65
	v_cvt_pk_bf16_f32 v102, v1, v49
	ds_write_b16 v85, v102 offset:256
	ds_write_b16_d16_hi v86, v102 offset:320
	v_mul_f32_e32 v33, v33, v65
	v_mul_f32_e32 v17, v17, v65
	v_cvt_pk_bf16_f32 v103, v33, v17
	ds_write_b16 v85, v103 offset:384
	ds_write_b16_d16_hi v86, v103 offset:448
	v_mul_f32_e32 v2, v2, v66
	v_mul_f32_e32 v50, v50, v66
	v_cvt_pk_bf16_f32 v104, v2, v50
	ds_write_b16 v85, v104 offset:512
	ds_write_b16_d16_hi v86, v104 offset:576
	v_mul_f32_e32 v34, v34, v66
	v_mul_f32_e32 v18, v18, v66
	v_cvt_pk_bf16_f32 v105, v34, v18
	ds_write_b16 v85, v105 offset:640
	ds_write_b16_d16_hi v86, v105 offset:704
	v_mul_f32_e32 v3, v3, v67
	v_mul_f32_e32 v51, v51, v67
	v_cvt_pk_bf16_f32 v106, v3, v51
	ds_write_b16 v85, v106 offset:768
	ds_write_b16_d16_hi v86, v106 offset:832
	v_mul_f32_e32 v35, v35, v67
	v_mul_f32_e32 v19, v19, v67
	v_cvt_pk_bf16_f32 v107, v35, v19
	ds_write_b16 v85, v107 offset:896
	ds_write_b16_d16_hi v86, v107 offset:960
	v_mul_f32_e32 v4, v4, v68
	v_mul_f32_e32 v52, v52, v68
	v_cvt_pk_bf16_f32 v100, v4, v52
	ds_write_b16 v85, v100 offset:2048
	ds_write_b16_d16_hi v86, v100 offset:2112
	v_mul_f32_e32 v36, v36, v68
	v_mul_f32_e32 v20, v20, v68
	v_cvt_pk_bf16_f32 v101, v36, v20
	ds_write_b16 v85, v101 offset:2176
	ds_write_b16_d16_hi v86, v101 offset:2240
	v_mul_f32_e32 v5, v5, v69
	v_mul_f32_e32 v53, v53, v69
	v_cvt_pk_bf16_f32 v102, v5, v53
	ds_write_b16 v85, v102 offset:2304
	ds_write_b16_d16_hi v86, v102 offset:2368
	v_mul_f32_e32 v37, v37, v69
	v_mul_f32_e32 v21, v21, v69
	v_cvt_pk_bf16_f32 v103, v37, v21
	ds_write_b16 v85, v103 offset:2432
	ds_write_b16_d16_hi v86, v103 offset:2496
	v_mul_f32_e32 v6, v6, v70
	v_mul_f32_e32 v54, v54, v70
	v_cvt_pk_bf16_f32 v104, v6, v54
; __device__ __forceinline__ bf16_t f2bf(float f) { return (bf16_t)(cvt_pk_bf16(f, 0.f) & 0xffffu); }
; __device__ __forceinline__ int crow(int r, int hi) { return (r & 3) + 8 * (r >> 2) + 4 * hi; }
; __device__ __forceinline__ void attn_unit(const bf16_t* __restrict__ Qb, const bf16_t* __restrict__ Kh, const bf16_t* __restrict__ Vh, bf16_t* __restrict__ Ob, int seq, char* lds) {
;     ...
;     if (hi == 0) li_l[r32] = l_reg; asm volatile("s_waitcnt lgkmcnt(0)" ::: "memory");
;     float rli[16];
; #pragma unroll
;     for (int r = 0; r < 16; ++r) rli[r] = __builtin_amdgcn_rcpf(li_l[crow(r, hi)]);
;     bf16_t* Ow = Ob + (size_t)(wid * QBLK) * 2048;
; #pragma unroll
;     for (int r = 0; r < 16; ++r) { const int orow = crow(r, hi);
; #pragma unroll
;         for (int d0 = 0; d0 < 4; ++d0) Ow[(size_t)orow * 2048 + d0 * 32 + r32] = f2bf(o[d0][r] * rli[r]); }
	ds_write_b16 v85, v104 offset:2560
	ds_write_b16_d16_hi v86, v104 offset:2624
	v_mul_f32_e32 v38, v38, v70
	v_mul_f32_e32 v22, v22, v70
	v_cvt_pk_bf16_f32 v105, v38, v22
	ds_write_b16 v85, v105 offset:2688
	ds_write_b16_d16_hi v86, v105 offset:2752
	v_mul_f32_e32 v7, v7, v71
	v_mul_f32_e32 v55, v55, v71
	v_cvt_pk_bf16_f32 v106, v7, v55
	ds_write_b16 v85, v106 offset:2816
	ds_write_b16_d16_hi v86, v106 offset:2880
	v_mul_f32_e32 v39, v39, v71
	v_mul_f32_e32 v23, v23, v71
	v_cvt_pk_bf16_f32 v107, v39, v23
	ds_write_b16 v85, v107 offset:2944
	ds_write_b16_d16_hi v86, v107 offset:3008
	v_mul_f32_e32 v8, v8, v74
	v_mul_f32_e32 v56, v56, v74
	v_cvt_pk_bf16_f32 v100, v8, v56
	ds_write_b16 v85, v100 offset:4096
	ds_write_b16_d16_hi v86, v100 offset:4160
	v_mul_f32_e32 v40, v40, v74
	v_mul_f32_e32 v24, v24, v74
	v_cvt_pk_bf16_f32 v101, v40, v24
	ds_write_b16 v85, v101 offset:4224
	ds_write_b16_d16_hi v86, v101 offset:4288
	v_mul_f32_e32 v9, v9, v75
	v_mul_f32_e32 v57, v57, v75
	v_cvt_pk_bf16_f32 v102, v9, v57
	ds_write_b16 v85, v102 offset:4352
	ds_write_b16_d16_hi v86, v102 offset:4416
	v_mul_f32_e32 v41, v41, v75
	v_mul_f32_e32 v25, v25, v75
	v_cvt_pk_bf16_f32 v103, v41, v25
	ds_write_b16 v85, v103 offset:4480
	ds_write_b16_d16_hi v86, v103 offset:4544
	v_mul_f32_e32 v10, v10, v76
	v_mul_f32_e32 v58, v58, v76
	v_cvt_pk_bf16_f32 v104, v10, v58
	ds_write_b16 v85, v104 offset:4608
	ds_write_b16_d16_hi v86, v104 offset:4672
	v_mul_f32_e32 v42, v42, v76
	v_mul_f32_e32 v26, v26, v76
	v_cvt_pk_bf16_f32 v105, v42, v26
	ds_write_b16 v85, v105 offset:4736
	ds_write_b16_d16_hi v86, v105 offset:4800
	v_mul_f32_e32 v11, v11, v77
	v_mul_f32_e32 v59, v59, v77
	v_cvt_pk_bf16_f32 v106, v11, v59
	ds_write_b16 v85, v106 offset:4864
	ds_write_b16_d16_hi v86, v106 offset:4928
	v_mul_f32_e32 v43, v43, v77
	v_mul_f32_e32 v27, v27, v77
	v_cvt_pk_bf16_f32 v107, v43, v27
	ds_write_b16 v85, v107 offset:4992
	ds_write_b16_d16_hi v86, v107 offset:5056
	v_mul_f32_e32 v12, v12, v78
	v_mul_f32_e32 v60, v60, v78
	v_cvt_pk_bf16_f32 v100, v12, v60
	ds_write_b16 v85, v100 offset:6144
	ds_write_b16_d16_hi v86, v100 offset:6208
	v_mul_f32_e32 v44, v44, v78
	v_mul_f32_e32 v28, v28, v78
	v_cvt_pk_bf16_f32 v101, v44, v28
	ds_write_b16 v85, v101 offset:6272
	ds_write_b16_d16_hi v86, v101 offset:6336
	v_mul_f32_e32 v13, v13, v79
	v_mul_f32_e32 v61, v61, v79
	v_cvt_pk_bf16_f32 v102, v13, v61
	ds_write_b16 v85, v102 offset:6400
	ds_write_b16_d16_hi v86, v102 offset:6464
	v_mul_f32_e32 v45, v45, v79
	v_mul_f32_e32 v29, v29, v79
	v_cvt_pk_bf16_f32 v103, v45, v29
	ds_write_b16 v85, v103 offset:6528
	ds_write_b16_d16_hi v86, v103 offset:6592
	v_mul_f32_e32 v14, v14, v80
	v_mul_f32_e32 v62, v62, v80
	v_cvt_pk_bf16_f32 v104, v14, v62
	ds_write_b16 v85, v104 offset:6656
	ds_write_b16_d16_hi v86, v104 offset:6720
	v_mul_f32_e32 v46, v46, v80
	v_mul_f32_e32 v30, v30, v80
	v_cvt_pk_bf16_f32 v105, v46, v30
	ds_write_b16 v85, v105 offset:6784
	ds_write_b16_d16_hi v86, v105 offset:6848
	v_mul_f32_e32 v15, v15, v81
	v_mul_f32_e32 v63, v63, v81
	v_cvt_pk_bf16_f32 v106, v15, v63
	ds_write_b16 v85, v106 offset:6912
	ds_write_b16_d16_hi v86, v106 offset:6976
	v_mul_f32_e32 v47, v47, v81
	v_mul_f32_e32 v31, v31, v81
	v_cvt_pk_bf16_f32 v107, v47, v31
	ds_write_b16 v85, v107 offset:7040
	ds_write_b16_d16_hi v86, v107 offset:7104
	s_waitcnt lgkmcnt(0)
	ds_read_b128 v[108:111], v93 offset:0
	ds_read_b128 v[112:115], v94 offset:1024
	ds_read_b128 v[116:119], v93 offset:2048
	ds_read_b128 v[120:123], v94 offset:3072
	ds_read_b128 v[124:127], v93 offset:4096
	ds_read_b128 v[128:131], v94 offset:5120
	ds_read_b128 v[132:135], v93 offset:6144
	ds_read_b128 v[136:139], v94 offset:7168
	s_waitcnt lgkmcnt(7)
	global_store_dwordx4 v95, v[108:111], s[2:3]
	s_waitcnt lgkmcnt(6)
	s_add_u32 s12, s2, 0x4000
	s_addc_u32 s13, s3, 0
	global_store_dwordx4 v95, v[112:115], s[12:13]
	s_waitcnt lgkmcnt(5)
	s_add_u32 s12, s2, 0x8000
	s_addc_u32 s13, s3, 0
	global_store_dwordx4 v95, v[116:119], s[12:13]
	s_waitcnt lgkmcnt(4)
	s_add_u32 s12, s2, 0xc000
	s_addc_u32 s13, s3, 0
	global_store_dwordx4 v95, v[120:123], s[12:13]
	s_waitcnt lgkmcnt(3)
	s_add_u32 s12, s2, 0x10000
	s_addc_u32 s13, s3, 0
	global_store_dwordx4 v95, v[124:127], s[12:13]
	s_waitcnt lgkmcnt(2)
	s_add_u32 s12, s2, 0x14000
	s_addc_u32 s13, s3, 0
	global_store_dwordx4 v95, v[128:131], s[12:13]
	s_waitcnt lgkmcnt(1)
	s_add_u32 s12, s2, 0x18000
	s_addc_u32 s13, s3, 0
	global_store_dwordx4 v95, v[132:135], s[12:13]
	s_waitcnt lgkmcnt(0)
	s_add_u32 s12, s2, 0x1c000
	s_addc_u32 s13, s3, 0
	global_store_dwordx4 v95, v[136:139], s[12:13]
	s_waitcnt vmcnt(63) expcnt(7) lgkmcnt(15)
	s_barrier
	s_mov_b64 s[2:3], 0
